# all eight GEMM K-loop heads aligned to 64 bytes (code placement), on top of v54
# speedup vs baseline: 1.0039x; 1.0011x over previous
; #define S xcd_barrier(bar);
; template <class Epi, bool ALIGN_EPI, bool ABLK = false>
; __device__ __forceinline__ void gemm_phase(PG8_LAS unsigned char* lds, const Gemm g, const StaticOrder& S, const Epi& E) {
;     ...
;         const bool has_next = S.next(ui + 1, nxt);
;         const char* nA = has_next ? PG8_ABASE(nxt) : cA; const char* nB = has_next ? PG8_BBASE(nxt) : cB;
;         for (int t = 0; t < nt; t += 2) {
;             const bool last = (t == nt - 2);
;             const char* a1 = cA + (size_t)(t + 1) * kstepA;
;             const char* a2 = last ? nA : cA + (size_t)(t + 2) * kstepA; const char* b2 = last ? nB : cB + (size_t)(t + 2) * kstepB;
;             const char* a3 = a2 + kstepA; const char* b3 = b2 + kstepB;
.LBB0_401:
	s_ashr_i32 s41, s40, 31
	s_lshl_b64 s[42:43], s[40:41], 19
	s_add_u32 s42, s11, s42
	s_addc_u32 s43, s54, s43
	s_and_b64 s[44:45], s[6:7], exec
	s_cselect_b32 s41, s43, s25
	s_cselect_b32 s66, s42, s24
	s_ashr_i32 s39, s38, 31
	s_lshl_b64 s[44:45], s[38:39], 19
	s_add_u32 s44, s12, s44
	s_addc_u32 s45, s13, s45
	s_and_b64 s[46:47], s[6:7], exec
	s_cselect_b32 s39, s45, s23
	s_cselect_b32 s67, s44, s22
	s_add_u32 s68, s22, 0x100
	s_addc_u32 s69, s23, 0
	s_mov_b32 s70, -2
	s_mov_b64 s[46:47], 0x10000
	s_mov_b64 s[82:83], s[24:25]
	.p2align 6

; template <class Epi, bool ALIGN_EPI, bool ABLK = false>
; __device__ __forceinline__ void gemm_phase(PG8_LAS unsigned char* lds, const Gemm g, const StaticOrder& S, const Epi& E) {
;     ...
;         if (!E.keep(cur)) {
; #pragma unroll
;             for (int a = 0; a < 2; ++a)
; #pragma unroll
;                 for (int b = 0; b < 2; ++b)
; #pragma unroll
;                     for (int m = 0; m < 4; ++m)
; #pragma unroll
;                         for (int n = 0; n < 2; ++n) acc[a][b][m][n] = (f32x4){0.f, 0.f, 0.f, 0.f};
;         }
;         cur = nxt; cA = nA; cB = nB; ++ui;
.LBB0_539:
	s_add_u32 s54, s50, 0x100
	s_addc_u32 s55, s51, 0
	s_add_u32 s50, s52, 0x10000
	v_mov_b32_e32 v2, 0
	s_addc_u32 s51, s53, 0
	s_mov_b32 s78, -2
	s_waitcnt lgkmcnt(0)
	v_mov_b32_e32 v3, v2
	v_mov_b32_e32 v4, v2
	v_mov_b32_e32 v5, v2
	v_mov_b32_e32 v6, v2
	v_mov_b32_e32 v7, v2
	v_mov_b32_e32 v8, v2
	v_mov_b32_e32 v9, v2
	v_mov_b32_e32 v18, v2
	v_mov_b32_e32 v19, v2
	v_mov_b32_e32 v20, v2
	v_mov_b32_e32 v21, v2
	v_mov_b32_e32 v22, v2
	v_mov_b32_e32 v23, v2
	v_mov_b32_e32 v24, v2
	v_mov_b32_e32 v25, v2
	v_mov_b32_e32 v34, v2
	v_mov_b32_e32 v35, v2
	v_mov_b32_e32 v36, v2
	v_mov_b32_e32 v37, v2
	v_mov_b32_e32 v38, v2
	v_mov_b32_e32 v39, v2
	v_mov_b32_e32 v40, v2
	v_mov_b32_e32 v41, v2
	v_mov_b32_e32 v50, v2
	v_mov_b32_e32 v51, v2
	v_mov_b32_e32 v52, v2
	v_mov_b32_e32 v53, v2
	v_mov_b32_e32 v54, v2
	v_mov_b32_e32 v55, v2
	v_mov_b32_e32 v56, v2
	v_mov_b32_e32 v57, v2
	v_mov_b32_e32 v10, v2
	v_mov_b32_e32 v11, v2
	v_mov_b32_e32 v12, v2
	v_mov_b32_e32 v13, v2
	v_mov_b32_e32 v14, v2
	v_mov_b32_e32 v15, v2
	v_mov_b32_e32 v16, v2
	v_mov_b32_e32 v17, v2
	v_mov_b32_e32 v26, v2
	v_mov_b32_e32 v27, v2
	v_mov_b32_e32 v28, v2
	v_mov_b32_e32 v29, v2
	v_mov_b32_e32 v30, v2
	v_mov_b32_e32 v31, v2
	v_mov_b32_e32 v32, v2
	v_mov_b32_e32 v33, v2
	v_mov_b32_e32 v42, v2
	v_mov_b32_e32 v43, v2
	v_mov_b32_e32 v44, v2
	v_mov_b32_e32 v45, v2
	v_mov_b32_e32 v46, v2
	v_mov_b32_e32 v47, v2
	v_mov_b32_e32 v48, v2
	v_mov_b32_e32 v49, v2
	v_mov_b32_e32 v58, v2
	v_mov_b32_e32 v59, v2
	v_mov_b32_e32 v60, v2
	v_mov_b32_e32 v61, v2
	v_mov_b32_e32 v62, v2
	v_mov_b32_e32 v63, v2
	v_mov_b32_e32 v64, v2
	v_mov_b32_e32 v65, v2
	v_mov_b32_e32 v66, v2
	v_mov_b32_e32 v67, v2
	v_mov_b32_e32 v68, v2
	v_mov_b32_e32 v69, v2
	v_mov_b32_e32 v70, v2
	v_mov_b32_e32 v71, v2
	v_mov_b32_e32 v72, v2
	v_mov_b32_e32 v73, v2
	v_mov_b32_e32 v82, v2
	v_mov_b32_e32 v83, v2
	v_mov_b32_e32 v84, v2
	v_mov_b32_e32 v85, v2
	v_mov_b32_e32 v86, v2
	v_mov_b32_e32 v87, v2
	v_mov_b32_e32 v88, v2
	v_mov_b32_e32 v89, v2
	v_mov_b32_e32 v102, v2
	v_mov_b32_e32 v103, v2
	v_mov_b32_e32 v104, v2
	v_mov_b32_e32 v105, v2
	v_mov_b32_e32 v106, v2
	v_mov_b32_e32 v107, v2
	v_mov_b32_e32 v108, v2
	v_mov_b32_e32 v109, v2
	v_mov_b32_e32 v130, v2
	v_mov_b32_e32 v131, v2
	v_mov_b32_e32 v132, v2
	v_mov_b32_e32 v133, v2
	v_mov_b32_e32 v138, v2
	v_mov_b32_e32 v139, v2
	v_mov_b32_e32 v140, v2
	v_mov_b32_e32 v141, v2
	v_mov_b32_e32 v74, v2
	v_mov_b32_e32 v75, v2
	v_mov_b32_e32 v76, v2
	v_mov_b32_e32 v77, v2
	v_mov_b32_e32 v78, v2
	v_mov_b32_e32 v79, v2
	v_mov_b32_e32 v80, v2
	v_mov_b32_e32 v81, v2
	v_mov_b32_e32 v90, v2
	v_mov_b32_e32 v91, v2
	v_mov_b32_e32 v92, v2
	v_mov_b32_e32 v93, v2
	v_mov_b32_e32 v94, v2
	v_mov_b32_e32 v95, v2
	v_mov_b32_e32 v96, v2
	v_mov_b32_e32 v97, v2
	v_mov_b32_e32 v114, v2
	v_mov_b32_e32 v115, v2
	v_mov_b32_e32 v116, v2
	v_mov_b32_e32 v117, v2
	v_mov_b32_e32 v118, v2
	v_mov_b32_e32 v119, v2
	v_mov_b32_e32 v120, v2
	v_mov_b32_e32 v121, v2
	v_mov_b32_e32 v158, v2
	v_mov_b32_e32 v159, v2
	v_mov_b32_e32 v160, v2
	v_mov_b32_e32 v161, v2
	v_mov_b32_e32 v162, v2
	v_mov_b32_e32 v163, v2
	v_mov_b32_e32 v164, v2
	v_mov_b32_e32 v165, v2
	.p2align 6

; #define S xcd_barrier(bar);
; template <class Epi, bool ALIGN_EPI, bool ABLK = false>
; __device__ __forceinline__ void gemm_phase(PG8_LAS unsigned char* lds, const Gemm g, const StaticOrder& S, const Epi& E) {
;     ...
;         const bool has_next = S.next(ui + 1, nxt);
;         const char* nA = has_next ? PG8_ABASE(nxt) : cA; const char* nB = has_next ? PG8_BBASE(nxt) : cB;
;         for (int t = 0; t < nt; t += 2) {
;             const bool last = (t == nt - 2);
;             const char* a1 = cA + (size_t)(t + 1) * kstepA;
;             const char* a2 = last ? nA : cA + (size_t)(t + 2) * kstepA; const char* b2 = last ? nB : cB + (size_t)(t + 2) * kstepB;
;             const char* a3 = a2 + kstepA; const char* b3 = b2 + kstepB;
.LBB0_817:
	s_ashr_i32 s57, s56, 31
	s_lshl_b64 s[10:11], s[56:57], 19
	s_add_u32 s58, s74, s10
	s_addc_u32 s59, s75, s11
	s_and_b64 s[10:11], s[8:9], exec
	s_cselect_b32 s33, s59, s39
	s_cselect_b32 s57, s58, s38
	s_ashr_i32 s55, s54, 31
	s_lshl_b64 s[10:11], s[54:55], 19
	s_add_u32 s60, s14, s10
	s_addc_u32 s61, s15, s11
	s_and_b64 s[10:11], s[8:9], exec
	s_cselect_b32 s55, s61, s37
	s_cselect_b32 s62, s60, s36
	s_add_u32 s63, s36, 0x100
	s_addc_u32 s64, s37, 0
	s_mov_b32 s65, -2
	s_mov_b64 s[10:11], 0x10000
	v_add_u32_e32 v248, 0x2000, v154
	v_add_u32_e32 v249, 0x4000, v154
	v_add_u32_e32 v250, 0x6000, v154
	v_add_u32_e32 v251, 0x8000, v154
	v_add_u32_e32 v252, 0xa000, v154
	v_add_u32_e32 v253, 0xc000, v154
	v_add_u32_e32 v152, 0xe000, v154
	v_add_u32_e32 v153, 0x10000, v197
	.p2align 6

; #define S xcd_barrier(bar);
; template <class Epi, bool ALIGN_EPI, bool ABLK = false>
; __device__ __forceinline__ void gemm_phase(PG8_LAS unsigned char* lds, const Gemm g, const StaticOrder& S, const Epi& E) {
;     ...
;         const bool has_next = S.next(ui + 1, nxt);
;         const char* nA = has_next ? PG8_ABASE(nxt) : cA; const char* nB = has_next ? PG8_BBASE(nxt) : cB;
;         for (int t = 0; t < nt; t += 2) {
;             const bool last = (t == nt - 2);
;             const char* a1 = cA + (size_t)(t + 1) * kstepA;
;             const char* a2 = last ? nA : cA + (size_t)(t + 2) * kstepA; const char* b2 = last ? nB : cB + (size_t)(t + 2) * kstepB;
;             const char* a3 = a2 + kstepA; const char* b3 = b2 + kstepB;
.LBB0_1982:
	s_ashr_i32 s55, s54, 31
	s_lshl_b64 s[56:57], s[54:55], 19
	s_add_u32 s56, s14, s56
	s_addc_u32 s57, s15, s57
	s_and_b64 s[58:59], s[6:7], exec
	s_cselect_b32 s55, s57, s27
	s_cselect_b32 s75, s56, s26
	s_ashr_i32 s53, s52, 31
	s_lshl_b64 s[58:59], s[52:53], 19
	s_add_u32 s58, s18, s58
	s_addc_u32 s59, s19, s59
	s_and_b64 s[60:61], s[6:7], exec
	s_cselect_b32 s53, s59, s25
	s_cselect_b32 s76, s58, s24
	s_add_u32 s77, s24, 0x100
	s_addc_u32 s78, s25, 0
	s_mov_b32 s79, -2
	s_mov_b64 s[60:61], 0x10000
	v_mov_b64_e32 v[130:131], v[138:139]
	.p2align 6

; #define S xcd_barrier(bar);
; template <class Epi, bool ALIGN_EPI, bool ABLK = false>
; __device__ __forceinline__ void gemm_phase(PG8_LAS unsigned char* lds, const Gemm g, const StaticOrder& S, const Epi& E) {
;     ...
;         const bool has_next = S.next(ui + 1, nxt);
;         const char* nA = has_next ? PG8_ABASE(nxt) : cA; const char* nB = has_next ? PG8_BBASE(nxt) : cB;
;         for (int t = 0; t < nt; t += 2) {
;             const bool last = (t == nt - 2);
;             const char* a1 = cA + (size_t)(t + 1) * kstepA;
;             const char* a2 = last ? nA : cA + (size_t)(t + 2) * kstepA; const char* b2 = last ? nB : cB + (size_t)(t + 2) * kstepB;
;             const char* a3 = a2 + kstepA; const char* b3 = b2 + kstepB;
.LBB0_2104:
	s_and_b32 s67, s66, 1
	s_cmp_eq_u32 s67, 0
	s_cselect_b32 s41, s19, s58
	s_cselect_b32 s46, s18, s57
	s_ashr_i32 s43, s42, 31
	s_lshl_b64 s[44:45], s[42:43], 19
	s_add_u32 s44, s46, s44
	s_addc_u32 s45, s41, s45
	s_and_b64 s[46:47], s[4:5], exec
	s_cselect_b32 s43, s45, s7
	s_cselect_b32 s69, s44, s6
	s_ashr_i32 s41, s40, 31
	s_lshl_b64 s[46:47], s[40:41], 20
	s_add_u32 s41, s14, s46
	s_addc_u32 s47, s15, s47
	s_lshl_b32 s46, s67, 11
	s_add_u32 s46, s41, s46
	s_addc_u32 s47, s47, 0
	s_and_b64 s[50:51], s[4:5], exec
	s_cselect_b32 s41, s47, s49
	s_cselect_b32 s70, s46, s48
	s_add_u32 s6, s6, 0x40080
	s_addc_u32 s7, s7, 0
	s_add_u32 s71, s48, 0x100
	s_addc_u32 s72, s49, 0
	s_mov_b32 s73, -2
	.p2align 6

; #define S xcd_barrier(bar);
; template <class Epi, bool ALIGN_EPI, bool ABLK = false>
; __device__ __forceinline__ void gemm_phase(PG8_LAS unsigned char* lds, const Gemm g, const StaticOrder& S, const Epi& E) {
;     ...
;         const bool has_next = S.next(ui + 1, nxt);
;         const char* nA = has_next ? PG8_ABASE(nxt) : cA; const char* nB = has_next ? PG8_BBASE(nxt) : cB;
;         for (int t = 0; t < nt; t += 2) {
;             const bool last = (t == nt - 2);
;             const char* a1 = cA + (size_t)(t + 1) * kstepA;
;             const char* a2 = last ? nA : cA + (size_t)(t + 2) * kstepA; const char* b2 = last ? nB : cB + (size_t)(t + 2) * kstepB;
;             const char* a3 = a2 + kstepA; const char* b3 = b2 + kstepB;
;     ...
;         if (!E.keep(cur)) {
; #pragma unroll
;             for (int a = 0; a < 2; ++a)
; #pragma unroll
;                 for (int b = 0; b < 2; ++b)
; #pragma unroll
;                     for (int m = 0; m < 4; ++m)
; #pragma unroll
;                         for (int n = 0; n < 2; ++n) acc[a][b][m][n] = (f32x4){0.f, 0.f, 0.f, 0.f};
;         }
;         cur = nxt; cA = nA; cB = nB; ++ui;
.LBB0_2288:
	s_ashr_i32 s51, s50, 31
	s_lshl_b64 s[52:53], s[50:51], 19
	s_add_u32 s52, s20, s52
	s_addc_u32 s53, s21, s53
	s_and_b64 s[54:55], s[6:7], exec
	s_cselect_b32 s51, s53, s59
	s_cselect_b32 s60, s52, s58
	s_ashr_i32 s49, s48, 31
	s_lshl_b64 s[54:55], s[48:49], 19
	s_add_u32 s54, s18, s54
	s_addc_u32 s55, s19, s55
	s_and_b64 s[80:81], s[6:7], exec
	s_cselect_b32 s49, s55, s57
	s_cselect_b32 s61, s54, s56
	s_add_u32 s80, s56, 0x100
	s_addc_u32 s81, s57, 0
	s_add_u32 s56, s58, 0x10000
	v_mov_b32_e32 v2, 0
	s_addc_u32 s57, s59, 0
	s_mov_b32 s82, -2
	s_waitcnt lgkmcnt(0)
	v_mov_b32_e32 v3, v2
	v_mov_b32_e32 v4, v2
	v_mov_b32_e32 v5, v2
	v_mov_b32_e32 v6, v2
	v_mov_b32_e32 v7, v2
	v_mov_b32_e32 v8, v2
	v_mov_b32_e32 v9, v2
	v_mov_b32_e32 v18, v2
	v_mov_b32_e32 v19, v2
	v_mov_b32_e32 v20, v2
	v_mov_b32_e32 v21, v2
	v_mov_b32_e32 v22, v2
	v_mov_b32_e32 v23, v2
	v_mov_b32_e32 v24, v2
	v_mov_b32_e32 v25, v2
	v_mov_b32_e32 v34, v2
	v_mov_b32_e32 v35, v2
	v_mov_b32_e32 v36, v2
	v_mov_b32_e32 v37, v2
	v_mov_b32_e32 v38, v2
	v_mov_b32_e32 v39, v2
	v_mov_b32_e32 v40, v2
	v_mov_b32_e32 v41, v2
	v_mov_b32_e32 v50, v2
	v_mov_b32_e32 v51, v2
	v_mov_b32_e32 v52, v2
	v_mov_b32_e32 v53, v2
	v_mov_b32_e32 v54, v2
	v_mov_b32_e32 v55, v2
	v_mov_b32_e32 v56, v2
	v_mov_b32_e32 v57, v2
	v_mov_b32_e32 v10, v2
	v_mov_b32_e32 v11, v2
	v_mov_b32_e32 v12, v2
	v_mov_b32_e32 v13, v2
	v_mov_b32_e32 v14, v2
	v_mov_b32_e32 v15, v2
	v_mov_b32_e32 v16, v2
	v_mov_b32_e32 v17, v2
	v_mov_b32_e32 v26, v2
	v_mov_b32_e32 v27, v2
	v_mov_b32_e32 v28, v2
	v_mov_b32_e32 v29, v2
	v_mov_b32_e32 v30, v2
	v_mov_b32_e32 v31, v2
	v_mov_b32_e32 v32, v2
	v_mov_b32_e32 v33, v2
	v_mov_b32_e32 v42, v2
	v_mov_b32_e32 v43, v2
	v_mov_b32_e32 v44, v2
	v_mov_b32_e32 v45, v2
	v_mov_b32_e32 v46, v2
	v_mov_b32_e32 v47, v2
	v_mov_b32_e32 v48, v2
	v_mov_b32_e32 v49, v2
	v_mov_b32_e32 v58, v2
	v_mov_b32_e32 v59, v2
	v_mov_b32_e32 v60, v2
	v_mov_b32_e32 v61, v2
	v_mov_b32_e32 v62, v2
	v_mov_b32_e32 v63, v2
	v_mov_b32_e32 v64, v2
	v_mov_b32_e32 v65, v2
	v_mov_b32_e32 v66, v2
	v_mov_b32_e32 v67, v2
	v_mov_b32_e32 v68, v2
	v_mov_b32_e32 v69, v2
	v_mov_b32_e32 v70, v2
	v_mov_b32_e32 v71, v2
	v_mov_b32_e32 v72, v2
	v_mov_b32_e32 v73, v2
	v_mov_b32_e32 v82, v2
	v_mov_b32_e32 v83, v2
	v_mov_b32_e32 v84, v2
	v_mov_b32_e32 v85, v2
	v_mov_b32_e32 v86, v2
	v_mov_b32_e32 v87, v2
	v_mov_b32_e32 v88, v2
	v_mov_b32_e32 v89, v2
	v_mov_b32_e32 v98, v2
	v_mov_b32_e32 v99, v2
	v_mov_b32_e32 v100, v2
	v_mov_b32_e32 v101, v2
	v_mov_b32_e32 v106, v2
	v_mov_b32_e32 v107, v2
	v_mov_b32_e32 v108, v2
	v_mov_b32_e32 v109, v2
	v_mov_b32_e32 v126, v2
	v_mov_b32_e32 v127, v2
	v_mov_b32_e32 v128, v2
	v_mov_b32_e32 v129, v2
	v_mov_b32_e32 v130, v2
	v_mov_b32_e32 v131, v2
	v_mov_b32_e32 v132, v2
	v_mov_b32_e32 v133, v2
	v_mov_b32_e32 v74, v2
	v_mov_b32_e32 v75, v2
	v_mov_b32_e32 v76, v2
	v_mov_b32_e32 v77, v2
	v_mov_b32_e32 v78, v2
	v_mov_b32_e32 v79, v2
	v_mov_b32_e32 v80, v2
	v_mov_b32_e32 v81, v2
	v_mov_b32_e32 v90, v2
	v_mov_b32_e32 v91, v2
	v_mov_b32_e32 v92, v2
	v_mov_b32_e32 v93, v2
	v_mov_b32_e32 v94, v2
	v_mov_b32_e32 v95, v2
	v_mov_b32_e32 v96, v2
	v_mov_b32_e32 v97, v2
	v_mov_b32_e32 v114, v2
	v_mov_b32_e32 v115, v2
	v_mov_b32_e32 v116, v2
	v_mov_b32_e32 v117, v2
	v_mov_b32_e32 v118, v2
	v_mov_b32_e32 v119, v2
	v_mov_b32_e32 v120, v2
	v_mov_b32_e32 v121, v2
	v_mov_b32_e32 v138, v2
	v_mov_b32_e32 v139, v2
	v_mov_b32_e32 v140, v2
	v_mov_b32_e32 v141, v2
	v_mov_b32_e32 v142, v2
	v_mov_b32_e32 v143, v2
	v_mov_b32_e32 v144, v2
	v_mov_b32_e32 v145, v2
	.p2align 6

; #define S xcd_barrier(bar);
; template <class Epi, bool ALIGN_EPI, bool ABLK = false>
; __device__ __forceinline__ void gemm_phase(PG8_LAS unsigned char* lds, const Gemm g, const StaticOrder& S, const Epi& E) {
;     ...
;         const bool has_next = S.next(ui + 1, nxt);
;         const char* nA = has_next ? PG8_ABASE(nxt) : cA; const char* nB = has_next ? PG8_BBASE(nxt) : cB;
;         for (int t = 0; t < nt; t += 2) {
;             const bool last = (t == nt - 2);
;             const char* a1 = cA + (size_t)(t + 1) * kstepA;
;             const char* a2 = last ? nA : cA + (size_t)(t + 2) * kstepA; const char* b2 = last ? nB : cB + (size_t)(t + 2) * kstepB;
;             const char* a3 = a2 + kstepA; const char* b3 = b2 + kstepB;
.LBB0_2494:
	s_ashr_i32 s53, s52, 31
	s_lshl_b64 s[54:55], s[52:53], 19
	s_add_u32 s54, s11, s54
	s_addc_u32 s55, s33, s55
	s_and_b64 s[56:57], s[6:7], exec
	s_cselect_b32 s53, s55, s25
	s_cselect_b32 s79, s54, s24
	s_ashr_i32 s51, s50, 31
	s_lshl_b64 s[56:57], s[50:51], 19
	s_add_u32 s56, s12, s56
	s_addc_u32 s57, s13, s57
	s_and_b64 s[58:59], s[6:7], exec
	s_cselect_b32 s51, s57, s23
	s_cselect_b32 s80, s56, s22
	s_add_u32 s81, s22, 0x100
	s_addc_u32 s82, s23, 0
	s_mov_b32 s83, -2
	s_mov_b64 s[58:59], 0x10000
	.p2align 6

; template <class Epi, bool ALIGN_EPI, bool ABLK = false>
; __device__ __forceinline__ void gemm_phase(PG8_LAS unsigned char* lds, const Gemm g, const StaticOrder& S, const Epi& E) {
;     ...
;         if (!E.keep(cur)) {
; #pragma unroll
;             for (int a = 0; a < 2; ++a)
; #pragma unroll
;                 for (int b = 0; b < 2; ++b)
; #pragma unroll
;                     for (int m = 0; m < 4; ++m)
; #pragma unroll
;                         for (int n = 0; n < 2; ++n) acc[a][b][m][n] = (f32x4){0.f, 0.f, 0.f, 0.f};
;         }
;         cur = nxt; cA = nA; cB = nB; ++ui;
.LBB0_2630:
	s_add_u32 s51, s52, 0x100
	s_addc_u32 s56, s53, 0
	s_add_u32 s52, s54, 0x10000
	v_mov_b32_e32 v2, 0
	s_addc_u32 s53, s55, 0
	s_mov_b32 s57, -2
	v_mov_b32_e32 v3, v2
	v_mov_b32_e32 v4, v2
	v_mov_b32_e32 v5, v2
	v_mov_b32_e32 v6, v2
	v_mov_b32_e32 v7, v2
	v_mov_b32_e32 v8, v2
	v_mov_b32_e32 v9, v2
	v_mov_b32_e32 v18, v2
	v_mov_b32_e32 v19, v2
	v_mov_b32_e32 v20, v2
	v_mov_b32_e32 v21, v2
	v_mov_b32_e32 v22, v2
	v_mov_b32_e32 v23, v2
	v_mov_b32_e32 v24, v2
	v_mov_b32_e32 v25, v2
	v_mov_b32_e32 v34, v2
	v_mov_b32_e32 v35, v2
	v_mov_b32_e32 v36, v2
	v_mov_b32_e32 v37, v2
	v_mov_b32_e32 v38, v2
	v_mov_b32_e32 v39, v2
	v_mov_b32_e32 v40, v2
	v_mov_b32_e32 v41, v2
	v_mov_b32_e32 v50, v2
	v_mov_b32_e32 v51, v2
	v_mov_b32_e32 v52, v2
	v_mov_b32_e32 v53, v2
	v_mov_b32_e32 v54, v2
	v_mov_b32_e32 v55, v2
	v_mov_b32_e32 v56, v2
	v_mov_b32_e32 v57, v2
	v_mov_b32_e32 v10, v2
	v_mov_b32_e32 v11, v2
	v_mov_b32_e32 v12, v2
	v_mov_b32_e32 v13, v2
	v_mov_b32_e32 v14, v2
	v_mov_b32_e32 v15, v2
	v_mov_b32_e32 v16, v2
	v_mov_b32_e32 v17, v2
	v_mov_b32_e32 v26, v2
	v_mov_b32_e32 v27, v2
	v_mov_b32_e32 v28, v2
	v_mov_b32_e32 v29, v2
	v_mov_b32_e32 v30, v2
	v_mov_b32_e32 v31, v2
	v_mov_b32_e32 v32, v2
	v_mov_b32_e32 v33, v2
	v_mov_b32_e32 v42, v2
	v_mov_b32_e32 v43, v2
	v_mov_b32_e32 v44, v2
	v_mov_b32_e32 v45, v2
	v_mov_b32_e32 v46, v2
	v_mov_b32_e32 v47, v2
	v_mov_b32_e32 v48, v2
	v_mov_b32_e32 v49, v2
	v_mov_b32_e32 v58, v2
	v_mov_b32_e32 v59, v2
	v_mov_b32_e32 v60, v2
	v_mov_b32_e32 v61, v2
	v_mov_b32_e32 v62, v2
	v_mov_b32_e32 v63, v2
	v_mov_b32_e32 v64, v2
	v_mov_b32_e32 v65, v2
	v_mov_b32_e32 v66, v2
	v_mov_b32_e32 v67, v2
	v_mov_b32_e32 v68, v2
	v_mov_b32_e32 v69, v2
	v_mov_b32_e32 v70, v2
	v_mov_b32_e32 v71, v2
	v_mov_b32_e32 v72, v2
	v_mov_b32_e32 v73, v2
	v_mov_b32_e32 v82, v2
	v_mov_b32_e32 v83, v2
	v_mov_b32_e32 v84, v2
	v_mov_b32_e32 v85, v2
	v_mov_b32_e32 v86, v2
	v_mov_b32_e32 v87, v2
	v_mov_b32_e32 v88, v2
	v_mov_b32_e32 v89, v2
	v_mov_b32_e32 v98, v2
	v_mov_b32_e32 v99, v2
	v_mov_b32_e32 v100, v2
	v_mov_b32_e32 v101, v2
	v_mov_b32_e32 v102, v2
	v_mov_b32_e32 v103, v2
	v_mov_b32_e32 v104, v2
	v_mov_b32_e32 v105, v2
	v_mov_b32_e32 v114, v2
	v_mov_b32_e32 v115, v2
	v_mov_b32_e32 v116, v2
	v_mov_b32_e32 v117, v2
	v_mov_b32_e32 v118, v2
	v_mov_b32_e32 v119, v2
	v_mov_b32_e32 v120, v2
	v_mov_b32_e32 v121, v2
	v_mov_b32_e32 v74, v2
	v_mov_b32_e32 v75, v2
	v_mov_b32_e32 v76, v2
	v_mov_b32_e32 v77, v2
	v_mov_b32_e32 v78, v2
	v_mov_b32_e32 v79, v2
	v_mov_b32_e32 v80, v2
	v_mov_b32_e32 v81, v2
	v_mov_b32_e32 v90, v2
	v_mov_b32_e32 v91, v2
	v_mov_b32_e32 v92, v2
	v_mov_b32_e32 v93, v2
	v_mov_b32_e32 v94, v2
	v_mov_b32_e32 v95, v2
	v_mov_b32_e32 v96, v2
	v_mov_b32_e32 v97, v2
	v_mov_b32_e32 v106, v2
	v_mov_b32_e32 v107, v2
	v_mov_b32_e32 v108, v2
	v_mov_b32_e32 v109, v2
	v_mov_b32_e32 v110, v2
	v_mov_b32_e32 v111, v2
	v_mov_b32_e32 v112, v2
	v_mov_b32_e32 v113, v2
	v_mov_b32_e32 v122, v2
	v_mov_b32_e32 v123, v2
	v_mov_b32_e32 v124, v2
	v_mov_b32_e32 v125, v2
	v_mov_b32_e32 v126, v2
	v_mov_b32_e32 v127, v2
	v_mov_b32_e32 v128, v2
	v_mov_b32_e32 v129, v2
	.p2align 6
